# retention: static s_setprio 1 for waves 0-3 during the phase (on v34)
# baseline (speedup 1.0000x reference)
; #define LAS __attribute__((address_space(3)))
; __device__ __forceinline__ int lane_id_asm() { int l; asm volatile("v_mbcnt_lo_u32_b32 %0, -1, 0\n\tv_mbcnt_hi_u32_b32 %0, -1, %0" : "=v"(l)); return l; }
; __device__ __forceinline__ void ret_mfma(const Params& P, LAS unsigned char* lds, int wave) {
;     ...
;     const int lane = lane_id_asm(), t = wave * 64 + lane, q32 = lane & 31, hf = lane >> 5, i16 = lane & 15, blk = (lane >> 4) & 1;
;     const int trrow = 8 * hf + (i16 >> 2), trcol = (16 * blk + 4 * (i16 & 3)) * 2;
;     for (int unit = blockIdx.x; unit < 256; unit += gridDim.x) {
;         const int xcd_ = unit & 7, idx_ = unit >> 3, bh = xcd_ * 4 + (idx_ >> 3), slice = idx_ & 7, b = bh >> 2, hh = bh & 3;
;         const float gam = 1.f - exp2f(-5.f - (float)hh), lg = log2f(gam), g64 = exp2f(lg * 64.f);
;         for (int i = t; i < 33792 / 16; i += NTHREADS) *(LAS u32x4*)(lds + ST_OFF + i * 16) = (u32x4){0u, 0u, 0u, 0u};
;         f32x16 st[2];
; #pragma unroll
;         for (int a = 0; a < 2; ++a)
; #pragma unroll
;             for (int i = 0; i < 16; ++i) st[a][i] = 0.f;
;         const size_t rb = (size_t)b * SEQ;
;         float dec[16];
;         { const int mblk = (wave & 3) >> 1, nblk = wave & 1, n = nblk * 32 + q32;
; #pragma unroll
;           for (int i = 0; i < 16; ++i) { const int mm = mblk * 32 + 8 * (i >> 2) + 4 * hf + (i & 3); const int dist = n > mm ? n - mm : mm - n;
;               dec[i] = wave < 4 ? __builtin_amdgcn_exp2f(lg * (float)(dist - (63 - mm))) : __builtin_amdgcn_exp2f(lg * (float)(n + 1)); } }
;         u32x4 pq[4], pkk[4], pvv;
;         const int vr = t >> 3, vc = t & 7;
; #pragma unroll
;         for (int i = 0; i < 4; ++i) { const int id = t + 512 * i, r = id >> 5, ch = id & 31;
;             pq[i] = *(const u32x4*)(QK + (rb + r) * 2048 + hh * 256 + ch * 8); pkk[i] = *(const u32x4*)(QK + (rb + r) * 2048 + 1024 + hh * 256 + ch * 8); }
;         pvv = *(const u32x4*)(V + (rb + vr) * 2048 + hh * 512 + slice * 64 + vc * 8);
.LBB0_246:
	s_or_b64 exec, exec, s[50:51]
	s_add_u32 s60, s54, 0x1f000000
	s_addc_u32 s61, s55, 0
	s_cmpk_gt_i32 s2, 0xff
	s_waitcnt lgkmcnt(0)
	s_barrier
	v_mbcnt_lo_u32_b32 v0, -1, 0
	v_mbcnt_hi_u32_b32 v0, -1, v0
	s_cbranch_scc1 .LBB0_270
	v_ashrrev_i32_e32 v3, 5, v0
	v_and_b32_e32 v8, 31, v0
	v_readlane_b32 s4, v254, 4
	s_cmpk_lt_u32 s3, 0x100
	v_lshlrev_b32_e32 v5, 3, v3
	v_lshrrev_b32_e32 v2, 2, v0
	v_and_or_b32 v84, s4, 32, v8
	s_cselect_b64 s[4:5], -1, 0
	s_cmpk_gt_u32 s3, 0xff
	v_add_u32_e32 v1, s64, v0
	v_and_or_b32 v6, v2, 3, v5
	v_lshlrev_b32_e32 v2, 2, v0
	v_and_b32_e32 v4, 16, v0
	s_cselect_b64 s[10:11], -1, 0
	s_lshl_b32 s6, s33, 4
	v_and_or_b32 v2, v2, 12, v4
	s_and_b32 s6, s6, 32
	v_lshlrev_b32_e32 v86, 2, v3
	v_ashrrev_i32_e32 v88, 3, v1
	s_movk_i32 s9, 0xc0
	v_lshlrev_b32_e32 v7, 1, v2
	v_add_u32_e32 v9, s6, v86
	v_mul_lo_u32 v13, v88, s9
	s_add_i32 s6, 0, 0x10800
	v_add_u32_e32 v13, s6, v13
	v_add_u32_e32 v148, s6, v7
	s_add_i32 s6, s64, 0
	s_add_i32 s16, 0, 0x16800
	s_add_i32 s7, 0, 0x1ec00
	v_add_u32_e32 v7, s6, v7
	s_add_i32 s6, s16, s64
	v_lshlrev_b32_e32 v149, 4, v3
	v_mul_u32_u24_e32 v15, 0x210, v84
	v_lshl_add_u32 v14, v8, 1, s6
	v_add3_u32 v150, 0, v15, v149
	s_movk_i32 s6, 0x90
	v_mov_b32_e32 v15, s7
	v_add_u32_e32 v2, 1, v84
	v_mad_u32_u24 v151, v84, s6, v15
	s_add_i32 s6, s33, -4
	v_cvt_f32_ubyte0_e32 v85, v2
	v_and_b32_e32 v10, 7, v0
	v_lshlrev_b32_e32 v2, 3, v0
	v_lshlrev_b32_e32 v11, 4, v0
	s_lshr_b32 s14, s6, 1
	v_cmp_lt_u32_e64 s[6:7], 31, v0
	v_sub_u32_e32 v0, v84, v9
	v_sub_u32_e32 v16, 0, v0
	v_max_i32_e32 v16, v0, v16
	s_movk_i32 s21, 0xffc1
	v_add3_u32 v16, v9, v16, s21
	v_cvt_f32_i32_e32 v152, v16
	v_xad_u32 v16, v9, -1, v84
	v_sub_u32_e32 v17, 0, v16
	v_max_i32_e32 v16, v16, v17
	s_movk_i32 s21, 0xffc2
	v_add3_u32 v16, v9, v16, s21
	v_cvt_f32_i32_e32 v153, v16
	v_add_u32_e32 v16, -2, v0
	v_sub_u32_e32 v17, 2, v0
	v_max_i32_e32 v16, v16, v17
	s_movk_i32 s21, 0xffc3
	v_add3_u32 v16, v9, v16, s21
	v_cvt_f32_i32_e32 v154, v16
	v_add_u32_e32 v16, -3, v0
	v_sub_u32_e32 v17, 3, v0
	v_max_i32_e32 v16, v16, v17
	s_movk_i32 s21, 0xffc4
	v_add3_u32 v16, v9, v16, s21
	v_cvt_f32_i32_e32 v155, v16
	v_add_u32_e32 v16, -8, v0
	v_sub_u32_e32 v17, 8, v0
	v_max_i32_e32 v16, v16, v17
	s_movk_i32 s21, 0xffc9
	v_add3_u32 v16, v9, v16, s21
	v_cvt_f32_i32_e32 v156, v16
	v_add_u32_e32 v16, -9, v0
	v_sub_u32_e32 v17, 9, v0
	v_max_i32_e32 v16, v16, v17
	s_movk_i32 s21, 0xffca
	v_add3_u32 v16, v9, v16, s21
	v_cvt_f32_i32_e32 v157, v16
	v_add_u32_e32 v16, -10, v0
	v_sub_u32_e32 v17, 10, v0
	v_max_i32_e32 v16, v16, v17
	s_movk_i32 s21, 0xffcb
	v_add3_u32 v16, v9, v16, s21
	v_cvt_f32_i32_e32 v158, v16
	v_add_u32_e32 v16, -11, v0
	v_sub_u32_e32 v17, 11, v0
	v_max_i32_e32 v16, v16, v17
	s_movk_i32 s21, 0xffcc
	v_add3_u32 v16, v9, v16, s21
	v_cvt_f32_i32_e32 v159, v16
	v_add_u32_e32 v16, -16, v0
	v_sub_u32_e32 v17, 16, v0
	v_max_i32_e32 v16, v16, v17
	s_movk_i32 s21, 0xffd1
	v_add3_u32 v16, v9, v16, s21
	v_cvt_f32_i32_e32 v160, v16
	v_subrev_u32_e32 v16, 17, v0
	v_sub_u32_e32 v17, 17, v0
	v_max_i32_e32 v16, v16, v17
	s_movk_i32 s21, 0xffd2
	v_add3_u32 v16, v9, v16, s21
	v_cvt_f32_i32_e32 v161, v16
	v_subrev_u32_e32 v16, 18, v0
	v_sub_u32_e32 v17, 18, v0
	v_max_i32_e32 v16, v16, v17
	s_movk_i32 s21, 0xffd3
	v_add3_u32 v16, v9, v16, s21
	v_cvt_f32_i32_e32 v162, v16
	v_subrev_u32_e32 v16, 19, v0
	v_sub_u32_e32 v17, 19, v0
	v_max_i32_e32 v16, v16, v17
	s_movk_i32 s21, 0xffd4
	v_add3_u32 v16, v9, v16, s21
	v_cvt_f32_i32_e32 v163, v16
	v_subrev_u32_e32 v16, 24, v0
	v_sub_u32_e32 v17, 24, v0
	v_max_i32_e32 v16, v16, v17
	s_movk_i32 s21, 0xffd9
	v_add3_u32 v16, v9, v16, s21
	v_cvt_f32_i32_e32 v164, v16
	v_subrev_u32_e32 v16, 25, v0
	v_sub_u32_e32 v17, 25, v0
	v_max_i32_e32 v16, v16, v17
	s_movk_i32 s21, 0xffda
	v_add3_u32 v16, v9, v16, s21
	v_cvt_f32_i32_e32 v165, v16
	v_subrev_u32_e32 v16, 26, v0
	v_sub_u32_e32 v17, 26, v0
	v_max_i32_e32 v16, v16, v17
	s_movk_i32 s21, 0xffdb
	v_add3_u32 v16, v9, v16, s21
	v_cvt_f32_i32_e32 v166, v16
	v_subrev_u32_e32 v16, 27, v0
	v_sub_u32_e32 v0, 27, v0
	v_max_i32_e32 v0, v16, v0
	s_movk_i32 s21, 0xffdc
	v_add3_u32 v0, v9, v0, s21
	s_movk_i32 s8, 0x840
	s_lshr_b32 s18, s3, 7
	v_cvt_f32_i32_e32 v167, v0
	v_add_u32_e32 v0, 0x200, v1
	v_cmp_gt_i32_e64 s[0:1], s8, v1
	v_ashrrev_i32_e32 v94, 5, v0
	v_add_u32_e32 v0, 0x400, v1
	v_mul_lo_u32 v3, v3, s8
	s_mul_i32 s8, s18, 0x4200
	s_movk_i32 s17, 0x210
	v_ashrrev_i32_e32 v92, 5, v1
	v_ashrrev_i32_e32 v96, 5, v0
	v_add_u32_e32 v0, 0x600, v1
	v_add_u32_e32 v169, 0xfffffe00, v1
	v_mov_b32_e32 v1, s8
	v_and_b32_e32 v2, 0xf8, v2
	v_and_b32_e32 v12, 0x1f0, v11
	v_ashrrev_i32_e32 v98, 5, v0
	v_mad_u32_u24 v1, v8, s17, v1
	s_mov_b32 s15, 0
	v_mov_b32_e32 v91, 0
	v_lshlrev_b32_e32 v4, 3, v10
	v_add_u32_e32 v12, 0, v12
	v_lshlrev_b32_e32 v10, 4, v10
	s_lshl_b32 s19, s18, 6
	v_add_u32_e32 v5, v151, v5
	v_lshl_add_u32 v15, s14, 6, v148
	s_lshl_b32 s20, s14, 5
	v_mul_lo_u32 v0, v92, s17
	v_mul_lo_u32 v9, v94, s17
	v_mul_lo_u32 v16, v96, s17
	v_mul_lo_u32 v17, v98, s17
	v_mul_lo_u32 v168, v6, s9
	v_mul_lo_u32 v6, v6, s17
	v_lshlrev_b32_e32 v90, 1, v2
	s_add_i32 s16, s16, s68
	v_add3_u32 v1, v1, v149, 0
	v_ashrrev_i32_e32 v89, 31, v88
	v_ashrrev_i32_e32 v87, 31, v86
	v_ashrrev_i32_e32 v93, 31, v92
	v_ashrrev_i32_e32 v95, 31, v94
	v_ashrrev_i32_e32 v97, 31, v96
	v_ashrrev_i32_e32 v99, 31, v98
	v_lshl_add_u64 v[100:101], s[44:45], 0, v[90:91]
	v_add_u32_e32 v170, s16, v11
	v_add_u32_e32 v171, 0xe400, v1
	v_add_u32_e32 v172, 0x8400, v1
	s_movk_i32 s24, 0x63f
	s_mov_b32 s25, 0xc2fc0000
	s_mov_b32 s26, 0x800000
	v_lshlrev_b32_e32 v90, 1, v2
	v_lshlrev_b32_e32 v102, 1, v4
	s_lshl_b64 s[16:17], s[14:15], 2
	s_lshl_b32 s27, s20, 1
	v_add_u32_e32 v173, v12, v0
	v_add_u32_e32 v174, v12, v9
	v_add_u32_e32 v175, v12, v16
	v_add_u32_e32 v176, v12, v17
	v_add_u32_e32 v177, v13, v10
	v_add_u32_e32 v178, s19, v5
	v_add_u32_e32 v179, v7, v6
	v_add_u32_e32 v180, v14, v3
	v_add_u32_e32 v181, v15, v168
	v_mov_b32_e32 v186, v91
	v_mov_b32_e32 v187, v91
	v_mov_b32_e32 v188, v91
	v_mov_b32_e32 v189, v91
	v_mov_b32_e32 v182, 0x42800000
	v_mov_b32_e32 v183, 0x42000000
	v_mbcnt_hi_u32_b32 v184, -1, v244
	v_and_b32_e32 v242, 31, v184
	v_mul_u32_u24_e32 v242, 0x210, v242
	v_lshrrev_b32_e32 v103, 5, v184
	v_lshl_add_u32 v242, v103, 3, v242
	v_add_u32_e32 v242, s64, v242
	v_add_u32_e32 v242, 0x16800, v242
	s_mov_b32 s28, s2
	s_cmp_lg_u64 s[10:11], 0
	s_cbranch_scc1 .Lret_noprio
	s_setprio 1
.Lret_noprio:
	s_branch .LBB0_249
.LBB0_248:
	s_add_i32 s28, s28, s56
	s_cmpk_gt_i32 s28, 0xff
	s_cbranch_scc1 .LBB0_270

; __device__ __forceinline__ unsigned xb_ld(unsigned* p)              { return __hip_atomic_load(p, __ATOMIC_RELAXED, __HIP_MEMORY_SCOPE_AGENT); }
; __device__ __forceinline__ void xcd_barrier_complete(unsigned* bar, unsigned x, unsigned& nloc, unsigned& nx) {
;     const unsigned G = gridDim.x * gridDim.y * gridDim.z;
;     unsigned sum, cnt, mine, sp = 0u;
;     for (;;) {
;         sum = 0u; cnt = 0u; mine = 0u;
; #pragma unroll
;         for (unsigned j = 0; j < 16; ++j) { const unsigned c = xb_ld(&bar[XB_XCNT(j)]); sum += c; cnt += (c > 0u) ? 1u : 0u; mine = (j == x) ? c : mine; }
; __device__ __forceinline__ void xcd_barrier(const XcdBarrier& b) {
;     asm volatile("s_waitcnt vmcnt(0)" ::: "memory");
;     __syncthreads();
;     if (threadIdx.x == 0) {
;         unsigned* bar = b.bar;
;         __builtin_amdgcn_s_waitcnt(0);
;         unsigned nloc = b.st[0], nx = b.st[1];
;         if (nloc == 0u) { xcd_barrier_complete(bar, b.x, nloc, nx); b.st[0] = nloc; b.st[1] = nx; }
.LBB0_270:
	s_setprio 0
	s_waitcnt vmcnt(0)
	s_barrier
	s_and_saveexec_b64 s[50:51], s[12:13]
	s_cbranch_execz .LBB0_314
	s_add_i32 s0, 0, 0x27fc0
	v_mov_b32_e32 v0, s0
	s_waitcnt vmcnt(0) expcnt(0) lgkmcnt(0)
	ds_read_b32 v2, v0
	s_add_i32 s0, 0, 0x27fc4
	v_mov_b32_e32 v0, s0
	ds_read_b32 v0, v0
	s_waitcnt lgkmcnt(1)
	v_cmp_ne_u32_e32 vcc, 0, v2
	s_cbranch_vccnz .LBB0_285
	v_readlane_b32 s0, v254, 0
	s_mul_i32 s24, s57, s0
	s_add_u32 s0, s54, 0xc00200
	s_addc_u32 s1, s55, 0
	s_add_u32 s6, s54, 0xc00400
	s_addc_u32 s7, s55, 0
	s_add_u32 s8, s54, 0xc00500
	s_addc_u32 s9, s55, 0
	s_add_u32 s10, s54, 0xc00600
	s_addc_u32 s11, s55, 0
	s_add_u32 s14, s54, 0xc00700
	s_addc_u32 s15, s55, 0
	s_add_u32 s16, s54, 0xc00800
	s_addc_u32 s17, s55, 0
	s_add_u32 s18, s54, 0xc00900
	s_addc_u32 s19, s55, 0
	s_add_u32 s20, s54, 0xc00a00
	s_addc_u32 s21, s55, 0
	s_add_u32 s22, s54, 0xc00b00
	s_addc_u32 s23, s55, 0
	s_add_u32 s26, s54, 0xc00c00
	s_addc_u32 s27, s55, 0
	s_add_u32 s28, s54, 0xc00d00
	s_addc_u32 s29, s55, 0
	s_add_u32 s30, s54, 0xc00e00
	s_addc_u32 s31, s55, 0
	s_add_u32 s34, s54, 0xc00f00
	s_addc_u32 s35, s55, 0
	s_add_u32 s62, s54, 0xc01000
	s_addc_u32 s63, s55, 0
	s_add_u32 s64, s54, 0xc01100
	s_addc_u32 s65, s55, 0
	s_add_u32 s66, s54, 0xc01200
	s_addc_u32 s67, s55, 0
	s_add_u32 s70, s54, 0xc01300
	s_addc_u32 s71, s55, 0
	s_mul_i32 s24, s24, s56
	s_mov_b32 s25, 1
	s_mov_b64 s[4:5], 0
	s_waitcnt lgkmcnt(0)
	v_mov_b64_e32 v[0:1], s[6:7]
	v_mov_b64_e32 v[2:3], s[8:9]
	v_mov_b64_e32 v[4:5], s[10:11]
	v_mov_b64_e32 v[6:7], s[14:15]
	v_mov_b64_e32 v[8:9], s[16:17]
	v_mov_b64_e32 v[10:11], s[18:19]
	v_mov_b64_e32 v[12:13], s[20:21]
	v_mov_b64_e32 v[14:15], s[22:23]
	v_mov_b64_e32 v[16:17], s[26:27]
	v_mov_b64_e32 v[18:19], s[28:29]
	v_mov_b64_e32 v[20:21], s[30:31]
	v_mov_b64_e32 v[22:23], s[34:35]
	v_mov_b64_e32 v[24:25], s[62:63]
	v_mov_b64_e32 v[26:27], s[64:65]
	v_mov_b64_e32 v[28:29], s[66:67]
	v_mov_b64_e32 v[30:31], s[70:71]
	s_branch .LBB0_275
